# QKV up-projection GEMM skips the all-zero K-tiles of the block-diagonal merged weight (per-tile K range: q tiles 4 K-tiles, kv tiles 2)
# speedup vs baseline: 1.0095x; 1.0095x over previous
.LBB0_456:
	s_add_u32 s3, s26, 0x14000000
	v_writelane_b32 v245, s3, 46
	s_addc_u32 s3, s27, 0
	v_writelane_b32 v245, s3, 47
	s_add_u32 s3, s26, 0x17000000
	v_writelane_b32 v245, s3, 48
	s_addc_u32 s3, s27, 0
	v_writelane_b32 v245, s3, 49
	s_add_u32 s3, s26, 0x1a000000
	v_writelane_b32 v245, s3, 50
	s_addc_u32 s3, s27, 0
	s_add_u32 s21, s26, 0x1c000000
	s_addc_u32 s34, s27, 0
	s_andn2_b64 vcc, exec, s[0:1]
	v_writelane_b32 v245, s3, 51
	s_cbranch_vccnz .LBB0_494
	v_bfe_i32 v3, v20, 27, 1
	v_lshlrev_b32_e32 v1, 4, v20
	v_lshrrev_b32_e32 v3, 22, v3
	v_add_u32_e32 v3, v1, v3
	v_and_b32_e32 v3, 0xfffffc00, v3
	v_sub_u32_e32 v3, v1, v3
	v_ashrrev_i32_e32 v2, 31, v20
	v_lshrrev_b32_e32 v4, 4, v3
	v_lshrrev_b32_e32 v2, 26, v2
	v_bitop3_b32 v3, v4, v3, 32 bitop3:0x6c
	v_add_u32_e32 v2, v20, v2
	v_ashrrev_i32_e32 v5, 31, v3
	v_ashrrev_i32_e32 v2, 6, v2
	v_lshrrev_b32_e32 v5, 26, v5
	v_lshlrev_b32_e32 v4, 3, v2
	v_add_u32_e32 v5, v3, v5
	v_and_b32_e32 v4, -16, v4
	v_ashrrev_i32_e32 v6, 6, v5
	v_lshlrev_b32_e32 v2, 5, v2
	v_add_u32_e32 v4, v6, v4
	v_and_b32_e32 v14, 32, v2
	v_and_b32_e32 v2, 0xc0, v5
	v_sub_u32_e32 v2, v3, v2
	v_mov_b32_e32 v3, 1
	v_lshlrev_b32_e32 v5, 1, v4
	v_lshrrev_b32_e32 v7, 2, v4
	v_and_b32_e32 v6, 3, v6
	s_mov_b32 s1, 0x7fffffe0
	v_ashrrev_i16_sdwa v2, v3, sext(v2) dst_sel:DWORD dst_unused:UNUSED_PAD src0_sel:DWORD src1_sel:BYTE_0
	v_and_b32_e32 v5, 24, v5
	v_and_b32_e32 v7, 4, v7
	v_and_or_b32 v6, v4, s1, v6
	v_bfe_i32 v15, v2, 0, 16
	v_or3_b32 v5, v6, v7, v5
	v_add_u32_e32 v2, v14, v15
	v_mul_lo_u32 v16, v4, s2
	v_mul_lo_u32 v4, v5, s2
	v_add_u32_e32 v1, 0x2000, v1
	v_add_lshl_u32 v220, v2, v16, 1
	v_add_lshl_u32 v222, v4, v2, 1
	v_ashrrev_i32_e32 v2, 31, v1
	v_lshrrev_b32_e32 v2, 22, v2
	v_add_u32_e32 v2, v1, v2
	v_ashrrev_i32_e32 v2, 10, v2
	v_mul_i32_i24_e32 v4, 0x400, v2
	v_sub_u32_e32 v1, v1, v4
	v_lshrrev_b32_e32 v4, 4, v1
	v_bitop3_b32 v1, v4, v1, 32 bitop3:0x6c
	v_ashrrev_i32_e32 v5, 31, v1
	v_lshrrev_b32_e32 v5, 26, v5
	s_ashr_i32 s3, s2, 31
	v_lshlrev_b32_e32 v4, 3, v2
	v_add_u32_e32 v5, v1, v5
	s_lshl_b64 s[8:9], s[2:3], 9
	s_ashr_i32 s5, s62, 31
	v_and_b32_e32 v4, -16, v4
	v_ashrrev_i32_e32 v6, 6, v5
	v_lshlrev_b32_e32 v2, 5, v2
	s_mul_i32 s5, s8, s5
	s_mul_hi_u32 s10, s8, s62
	s_ashr_i32 s12, s64, 31
	v_add_u32_e32 v4, v6, v4
	v_and_b32_e32 v17, 32, v2
	v_and_b32_e32 v2, 0xc0, v5
	v_and_b32_e32 v5, 3, v6
	s_add_i32 s5, s10, s5
	s_lshr_b64 s[10:11], s[2:3], 23
	s_mul_i32 s12, s8, s12
	s_mul_hi_u32 s13, s8, s64
	v_and_or_b32 v5, v4, s1, v5
	s_ashr_i32 s1, s4, 6
	s_mul_i32 s11, s10, s62
	s_add_i32 s12, s13, s12
	s_mul_i32 s10, s10, s64
	s_ashr_i32 s0, s4, 8
	v_sub_u32_e32 v1, v1, v2
	s_lshl_b64 s[6:7], s[2:3], 8
	s_lshl_b32 s44, s1, 10
	s_add_i32 s5, s5, s11
	s_add_i32 s12, s12, s10
	s_mul_i32 s10, s8, s64
	v_readlane_b32 s14, v245, 18
	v_ashrrev_i16_sdwa v1, v3, sext(v1) dst_sel:DWORD dst_unused:UNUSED_PAD src0_sel:DWORD src1_sel:BYTE_0
	v_lshlrev_b32_e32 v2, 1, v4
	v_lshrrev_b32_e32 v3, 2, v4
	v_readlane_b32 s15, v245, 19
	s_add_u32 s58, s14, s10
	v_and_b32_e32 v2, 24, v2
	v_and_b32_e32 v3, 4, v3
	s_addc_u32 s59, s15, s12
	s_cmp_lt_i32 s64, 3
	s_cselect_b32 s98, 0, 0x200
	s_add_u32 s58, s58, s98
	s_addc_u32 s59, s59, 0
	s_add_i32 s45, s44, 0
	v_bfe_i32 v18, v1, 0, 16
	v_or3_b32 v2, v5, v3, v2
	s_add_i32 m0, s45, 0x10000
	v_add_u32_e32 v1, v17, v18
	v_mul_lo_u32 v2, v2, s2
	global_load_lds_dwordx4 v222, s[58:59]
	s_add_i32 m0, s45, 0x12000
	v_add_lshl_u32 v226, v2, v1, 1
	s_add_u32 s12, s58, s6
	global_load_lds_dwordx4 v226, s[58:59]
	s_addc_u32 s13, s59, s7
	s_add_i32 m0, s45, 0x14000
	s_mul_i32 s11, s8, s62
	global_load_lds_dwordx4 v222, s[12:13]
	s_add_i32 m0, s45, 0x16000
	s_add_u32 s56, s21, s11
	s_addc_u32 s57, s34, s5
	s_cmp_lt_i32 s64, 3
	s_cselect_b32 s98, 0, 0x200
	s_add_u32 s56, s56, s98
	s_addc_u32 s57, s57, 0
	s_add_i32 s46, s45, 0x2000
	v_mul_lo_u32 v19, v4, s2
	global_load_lds_dwordx4 v226, s[12:13]
	s_mov_b32 m0, s45
	s_add_u32 s10, s56, s6
	v_add_lshl_u32 v224, v1, v19, 1
	global_load_lds_dwordx4 v220, s[56:57]
	s_mov_b32 m0, s46
	s_addc_u32 s11, s57, s7
	s_add_i32 s47, s45, 0x4000
	global_load_lds_dwordx4 v224, s[56:57]
	s_mov_b32 m0, s47
	s_add_i32 s48, s45, 0x6000
	global_load_lds_dwordx4 v220, s[10:11]
	s_mov_b32 m0, s48
	v_mov_b32_e32 v229, 0
	global_load_lds_dwordx4 v224, s[10:11]
	v_mov_b32_e32 v223, v229
	v_mov_b32_e32 v227, v229
	v_mov_b32_e32 v221, v229
	v_mov_b32_e32 v225, v229
	s_cmp_eq_u32 s0, 1
	s_mov_b32 s11, 0
	v_lshl_add_u64 v[10:11], s[58:59], 0, v[222:223]
	v_lshl_add_u64 v[6:7], s[58:59], 0, v[226:227]
	v_lshl_add_u64 v[4:5], s[12:13], 0, v[222:223]
	v_lshl_add_u64 v[2:3], s[12:13], 0, v[226:227]
	v_lshl_add_u64 v[8:9], s[56:57], 0, v[220:221]
	s_cselect_b64 s[12:13], -1, 0
	s_cmp_lg_u32 s0, 1
	v_lshl_add_u64 v[12:13], s[56:57], 0, v[224:225]
	s_cbranch_scc1 .LBB0_459
	s_barrier

.LBB0_464:
	s_nop 0
	v_cndmask_b32_e64 v2, 0, 1, s[4:5]
	v_cmp_ne_u32_e64 s[2:3], 1, v2
	s_andn2_b64 vcc, exec, s[4:5]
	s_mov_b64 s[4:5], s[56:57]
	s_cbranch_vccnz .LBB0_466
	s_ashr_i32 s0, s89, 31
	s_mul_hi_u32 s1, s8, s89
	s_mul_i32 s0, s8, s0
	s_add_i32 s0, s1, s0
	s_mul_i32 s1, s9, s89
	s_add_i32 s0, s0, s1
	s_mul_i32 s1, s8, s89
	s_add_u32 s4, s21, s1
	s_addc_u32 s5, s34, s0
	s_cmp_lt_i32 s88, 3
	s_cselect_b32 s98, 0, 0x200
	s_add_u32 s4, s4, s98
	s_addc_u32 s5, s5, 0
.LBB0_466:
	s_and_b64 vcc, exec, s[2:3]
	s_mov_b64 s[54:55], s[58:59]
	s_cbranch_vccnz .LBB0_468
	s_ashr_i32 s0, s88, 31
	s_mul_hi_u32 s1, s8, s88
	s_mul_i32 s0, s8, s0
	s_add_i32 s0, s1, s0
	s_mul_i32 s1, s9, s88
	s_add_i32 s0, s0, s1
	s_mul_i32 s1, s8, s88
	v_readlane_b32 s38, v245, 18
	v_readlane_b32 s39, v245, 19
	s_add_u32 s54, s38, s1
	s_addc_u32 s55, s39, s0
	s_cmp_lt_i32 s88, 3
	s_cselect_b32 s98, 0, 0x200
	s_add_u32 s54, s54, s98
	s_addc_u32 s55, s55, 0
.LBB0_468:
	v_mov_b32_e32 v3, v0
	v_mov_b64_e32 v[194:195], v[2:3]
	v_mov_b64_e32 v[172:173], v[2:3]
	v_mov_b64_e32 v[150:151], v[2:3]
	v_mov_b64_e32 v[196:197], v[2:3]
	v_mov_b64_e32 v[174:175], v[2:3]
	v_mov_b64_e32 v[152:153], v[2:3]
	v_mov_b64_e32 v[216:217], v[2:3]
	v_mov_b64_e32 v[210:211], v[2:3]
	v_mov_b64_e32 v[204:205], v[2:3]
	v_mov_b64_e32 v[166:167], v[2:3]
	v_mov_b64_e32 v[160:161], v[2:3]
	v_mov_b64_e32 v[198:199], v[2:3]
	v_mov_b64_e32 v[188:189], v[2:3]
	v_mov_b64_e32 v[182:183], v[2:3]
	v_mov_b64_e32 v[176:177], v[2:3]
	v_mov_b64_e32 v[154:155], v[2:3]
	v_mov_b64_e32 v[144:145], v[2:3]
	v_mov_b64_e32 v[138:139], v[2:3]
	v_mov_b64_e32 v[132:133], v[2:3]
	v_mov_b64_e32 v[218:219], v[2:3]
	v_mov_b64_e32 v[212:213], v[2:3]
	v_mov_b64_e32 v[206:207], v[2:3]
	v_mov_b64_e32 v[168:169], v[2:3]
	v_mov_b64_e32 v[162:163], v[2:3]
	v_mov_b64_e32 v[200:201], v[2:3]
	v_mov_b64_e32 v[190:191], v[2:3]
	v_mov_b64_e32 v[184:185], v[2:3]
	v_mov_b64_e32 v[178:179], v[2:3]
	v_mov_b64_e32 v[156:157], v[2:3]
	v_mov_b64_e32 v[146:147], v[2:3]
	v_mov_b64_e32 v[140:141], v[2:3]
	v_mov_b64_e32 v[134:135], v[2:3]
	s_andn2_b64 vcc, exec, s[16:17]
	v_mov_b32_e32 v129, v0
	v_mov_b32_e32 v128, v0
	v_mov_b32_e32 v127, v0
	v_mov_b32_e32 v125, v0
	v_mov_b32_e32 v124, v0
	v_mov_b32_e32 v123, v0
	v_mov_b32_e32 v121, v0
	v_mov_b32_e32 v120, v0
	v_mov_b32_e32 v119, v0
	v_mov_b32_e32 v117, v0
	v_mov_b32_e32 v116, v0
	v_mov_b32_e32 v115, v0
	v_mov_b32_e32 v113, v0
	v_mov_b32_e32 v112, v0
	v_mov_b32_e32 v111, v0
	v_mov_b32_e32 v109, v0
	v_mov_b32_e32 v108, v0
	v_mov_b32_e32 v107, v0
	v_mov_b32_e32 v105, v0
	v_mov_b32_e32 v104, v0
	v_mov_b32_e32 v103, v0
	v_mov_b32_e32 v101, v0
	v_mov_b32_e32 v100, v0
	v_mov_b32_e32 v99, v0
	v_mov_b32_e32 v65, v0
	v_mov_b32_e32 v64, v0
	v_mov_b32_e32 v63, v0
	v_mov_b32_e32 v61, v0
	v_mov_b32_e32 v60, v0
	v_mov_b32_e32 v59, v0
	v_mov_b32_e32 v57, v0
	v_mov_b32_e32 v56, v0
	v_mov_b32_e32 v55, v0
	v_mov_b32_e32 v53, v0
	v_mov_b32_e32 v52, v0
	v_mov_b32_e32 v51, v0
	v_mov_b32_e32 v49, v0
	v_mov_b32_e32 v48, v0
	v_mov_b32_e32 v47, v0
	v_mov_b32_e32 v45, v0
	v_mov_b32_e32 v44, v0
	v_mov_b32_e32 v43, v0
	v_mov_b32_e32 v41, v0
	v_mov_b32_e32 v40, v0
	v_mov_b32_e32 v39, v0
	v_mov_b32_e32 v37, v0
	v_mov_b32_e32 v36, v0
	v_mov_b32_e32 v35, v0
	v_mov_b32_e32 v97, v0
	v_mov_b32_e32 v96, v0
	v_mov_b32_e32 v95, v0
	v_mov_b32_e32 v93, v0
	v_mov_b32_e32 v92, v0
	v_mov_b32_e32 v91, v0
	v_mov_b32_e32 v89, v0
	v_mov_b32_e32 v88, v0
	v_mov_b32_e32 v87, v0
	v_mov_b32_e32 v85, v0
	v_mov_b32_e32 v84, v0
	v_mov_b32_e32 v83, v0
	v_mov_b32_e32 v81, v0
	v_mov_b32_e32 v80, v0
	v_mov_b32_e32 v79, v0
	v_mov_b32_e32 v77, v0
	v_mov_b32_e32 v76, v0
	v_mov_b32_e32 v75, v0
	v_mov_b32_e32 v73, v0
	v_mov_b32_e32 v72, v0
	v_mov_b32_e32 v71, v0
	v_mov_b32_e32 v69, v0
	v_mov_b32_e32 v68, v0
	v_mov_b32_e32 v67, v0
	v_mov_b32_e32 v33, v0
	v_mov_b32_e32 v32, v0
	v_mov_b32_e32 v31, v0
	v_mov_b32_e32 v29, v0
	v_mov_b32_e32 v28, v0
	v_mov_b32_e32 v27, v0
	v_mov_b32_e32 v25, v0
	v_mov_b32_e32 v24, v0
	v_mov_b32_e32 v23, v0
	v_mov_b32_e32 v21, v0
	v_mov_b32_e32 v20, v0
	v_mov_b32_e32 v19, v0
	v_mov_b32_e32 v17, v0
	v_mov_b32_e32 v16, v0
	v_mov_b32_e32 v15, v0
	v_mov_b32_e32 v13, v0
	v_mov_b32_e32 v12, v0
	v_mov_b32_e32 v11, v0
	v_mov_b32_e32 v9, v0
	v_mov_b32_e32 v8, v0
	v_mov_b32_e32 v7, v0
	v_mov_b32_e32 v5, v0
	v_mov_b32_e32 v4, v0
	v_mov_b64_e32 v[214:215], v[0:1]
	v_mov_b64_e32 v[216:217], v[0:1]
	v_mov_b64_e32 v[208:209], v[0:1]
	v_mov_b64_e32 v[210:211], v[0:1]
	v_mov_b64_e32 v[202:203], v[0:1]
	v_mov_b64_e32 v[204:205], v[0:1]
	v_mov_b64_e32 v[192:193], v[0:1]
	v_mov_b64_e32 v[194:195], v[0:1]
	v_mov_b64_e32 v[170:171], v[0:1]
	v_mov_b64_e32 v[172:173], v[0:1]
	v_mov_b64_e32 v[164:165], v[0:1]
	v_mov_b64_e32 v[166:167], v[0:1]
	v_mov_b64_e32 v[158:159], v[0:1]
	v_mov_b64_e32 v[160:161], v[0:1]
	v_mov_b64_e32 v[148:149], v[0:1]
	v_mov_b64_e32 v[150:151], v[0:1]
	v_mov_b64_e32 v[196:197], v[0:1]
	v_mov_b64_e32 v[198:199], v[0:1]
	v_mov_b64_e32 v[186:187], v[0:1]
	v_mov_b64_e32 v[188:189], v[0:1]
	v_mov_b64_e32 v[180:181], v[0:1]
	v_mov_b64_e32 v[182:183], v[0:1]
	v_mov_b64_e32 v[174:175], v[0:1]
	v_mov_b64_e32 v[176:177], v[0:1]
	v_mov_b64_e32 v[152:153], v[0:1]
	v_mov_b64_e32 v[154:155], v[0:1]
	v_mov_b64_e32 v[142:143], v[0:1]
	v_mov_b64_e32 v[144:145], v[0:1]
	v_mov_b64_e32 v[136:137], v[0:1]
	v_mov_b64_e32 v[138:139], v[0:1]
	v_mov_b64_e32 v[130:131], v[0:1]
	v_mov_b64_e32 v[132:133], v[0:1]
	s_cbranch_vccnz .LBB0_472
	s_add_u32 s56, s56, 0x80
	s_addc_u32 s57, s57, 0
	s_add_u32 s0, s58, 0x100
	s_addc_u32 s1, s59, 0
	s_mov_b32 s10, 0
	s_cmp_lt_i32 s64, 3
	s_cselect_b32 s49, 4, 2
	s_add_i32 s63, s49, -2
	v_mov_b32_e32 v2, v0
	v_mov_b32_e32 v3, v0
	v_mov_b32_e32 v4, v0
	v_mov_b32_e32 v5, v0
	v_mov_b32_e32 v6, v0
	v_mov_b32_e32 v7, v0
	v_mov_b32_e32 v8, v0
	v_mov_b32_e32 v9, v0
	v_mov_b32_e32 v10, v0
	v_mov_b32_e32 v11, v0
	v_mov_b32_e32 v12, v0
	v_mov_b32_e32 v13, v0
	v_mov_b32_e32 v14, v0
	v_mov_b32_e32 v15, v0
	v_mov_b32_e32 v16, v0
	v_mov_b32_e32 v17, v0
	v_mov_b32_e32 v18, v0
	v_mov_b32_e32 v19, v0
	v_mov_b32_e32 v20, v0
	v_mov_b32_e32 v21, v0
	v_mov_b32_e32 v22, v0
	v_mov_b32_e32 v23, v0
	v_mov_b32_e32 v24, v0
	v_mov_b32_e32 v25, v0
	v_mov_b32_e32 v26, v0
	v_mov_b32_e32 v27, v0
	v_mov_b32_e32 v28, v0
	v_mov_b32_e32 v29, v0
	v_mov_b32_e32 v30, v0
	v_mov_b32_e32 v31, v0
	v_mov_b32_e32 v32, v0
	v_mov_b32_e32 v33, v0
	v_mov_b32_e32 v66, v0
	v_mov_b32_e32 v67, v0
	v_mov_b32_e32 v68, v0
	v_mov_b32_e32 v69, v0
	v_mov_b32_e32 v70, v0
	v_mov_b32_e32 v71, v0
	v_mov_b32_e32 v72, v0
	v_mov_b32_e32 v73, v0
	v_mov_b32_e32 v74, v0
	v_mov_b32_e32 v75, v0
	v_mov_b32_e32 v76, v0
	v_mov_b32_e32 v77, v0
	v_mov_b32_e32 v78, v0
	v_mov_b32_e32 v79, v0
	v_mov_b32_e32 v80, v0
	v_mov_b32_e32 v81, v0
	v_mov_b32_e32 v82, v0
	v_mov_b32_e32 v83, v0
	v_mov_b32_e32 v84, v0
	v_mov_b32_e32 v85, v0
	v_mov_b32_e32 v86, v0
	v_mov_b32_e32 v87, v0
	v_mov_b32_e32 v88, v0
	v_mov_b32_e32 v89, v0
	v_mov_b32_e32 v90, v0
	v_mov_b32_e32 v91, v0
	v_mov_b32_e32 v92, v0
	v_mov_b32_e32 v93, v0
	v_mov_b32_e32 v94, v0
	v_mov_b32_e32 v95, v0
	v_mov_b32_e32 v96, v0
	v_mov_b32_e32 v97, v0
	v_mov_b32_e32 v34, v0
	v_mov_b32_e32 v35, v0
	v_mov_b32_e32 v36, v0
	v_mov_b32_e32 v37, v0
	v_mov_b32_e32 v38, v0
	v_mov_b32_e32 v39, v0
	v_mov_b32_e32 v40, v0
	v_mov_b32_e32 v41, v0
	v_mov_b32_e32 v42, v0
	v_mov_b32_e32 v43, v0
	v_mov_b32_e32 v44, v0
	v_mov_b32_e32 v45, v0
	v_mov_b32_e32 v46, v0
	v_mov_b32_e32 v47, v0
	v_mov_b32_e32 v48, v0
	v_mov_b32_e32 v49, v0
	v_mov_b32_e32 v50, v0
	v_mov_b32_e32 v51, v0
	v_mov_b32_e32 v52, v0
	v_mov_b32_e32 v53, v0
	v_mov_b32_e32 v54, v0
	v_mov_b32_e32 v55, v0
	v_mov_b32_e32 v56, v0
	v_mov_b32_e32 v57, v0
	v_mov_b32_e32 v58, v0
	v_mov_b32_e32 v59, v0
	v_mov_b32_e32 v60, v0
	v_mov_b32_e32 v61, v0
	v_mov_b32_e32 v62, v0
	v_mov_b32_e32 v63, v0
	v_mov_b32_e32 v64, v0
	v_mov_b32_e32 v65, v0
	v_mov_b32_e32 v98, v0
	v_mov_b32_e32 v99, v0
	v_mov_b32_e32 v100, v0
	v_mov_b32_e32 v101, v0
	v_mov_b32_e32 v102, v0
	v_mov_b32_e32 v103, v0
	v_mov_b32_e32 v104, v0
	v_mov_b32_e32 v105, v0
	v_mov_b32_e32 v106, v0
	v_mov_b32_e32 v107, v0
	v_mov_b32_e32 v108, v0
	v_mov_b32_e32 v109, v0
	v_mov_b32_e32 v110, v0
	v_mov_b32_e32 v111, v0
	v_mov_b32_e32 v112, v0
	v_mov_b32_e32 v113, v0
	v_mov_b32_e32 v114, v0
	v_mov_b32_e32 v115, v0
	v_mov_b32_e32 v116, v0
	v_mov_b32_e32 v117, v0
	v_mov_b32_e32 v118, v0
	v_mov_b32_e32 v119, v0
	v_mov_b32_e32 v120, v0
	v_mov_b32_e32 v121, v0
	v_mov_b32_e32 v122, v0
	v_mov_b32_e32 v123, v0
	v_mov_b32_e32 v124, v0
	v_mov_b32_e32 v125, v0
	v_mov_b32_e32 v126, v0
	v_mov_b32_e32 v127, v0
	v_mov_b32_e32 v128, v0
	v_mov_b32_e32 v129, v0

.LBB0_1746:
	s_andn2_b64 vcc, exec, s[0:1]
	s_cbranch_vccnz .LBB0_1784
	v_bfe_i32 v3, v14, 27, 1
	v_lshlrev_b32_e32 v1, 4, v14
	v_lshrrev_b32_e32 v3, 22, v3
	v_add_u32_e32 v3, v1, v3
	v_and_b32_e32 v3, 0xfffffc00, v3
	v_sub_u32_e32 v3, v1, v3
	v_ashrrev_i32_e32 v2, 31, v14
	v_lshrrev_b32_e32 v4, 4, v3
	v_lshrrev_b32_e32 v2, 26, v2
	v_bitop3_b32 v3, v4, v3, 32 bitop3:0x6c
	v_add_u32_e32 v2, v14, v2
	v_ashrrev_i32_e32 v5, 31, v3
	v_ashrrev_i32_e32 v2, 6, v2
	v_lshrrev_b32_e32 v5, 26, v5
	v_lshlrev_b32_e32 v4, 3, v2
	v_add_u32_e32 v5, v3, v5
	v_and_b32_e32 v4, -16, v4
	v_ashrrev_i32_e32 v6, 6, v5
	v_lshlrev_b32_e32 v2, 5, v2
	v_add_u32_e32 v4, v6, v4
	v_and_b32_e32 v15, 32, v2
	v_and_b32_e32 v2, 0xc0, v5
	v_sub_u32_e32 v2, v3, v2
	v_mov_b32_e32 v3, 1
	v_lshlrev_b32_e32 v5, 1, v4
	v_lshrrev_b32_e32 v7, 2, v4
	v_and_b32_e32 v6, 3, v6
	s_mov_b32 s1, 0x7fffffe0
	v_ashrrev_i16_sdwa v2, v3, sext(v2) dst_sel:DWORD dst_unused:UNUSED_PAD src0_sel:DWORD src1_sel:BYTE_0
	v_and_b32_e32 v5, 24, v5
	v_and_b32_e32 v7, 4, v7
	v_and_or_b32 v6, v4, s1, v6
	v_bfe_i32 v16, v2, 0, 16
	v_or3_b32 v5, v6, v7, v5
	v_add_u32_e32 v2, v15, v16
	v_mul_lo_u32 v17, v4, s2
	v_mul_lo_u32 v4, v5, s2
	v_add_u32_e32 v1, 0x2000, v1
	v_add_lshl_u32 v220, v2, v17, 1
	v_add_lshl_u32 v222, v4, v2, 1
	v_ashrrev_i32_e32 v2, 31, v1
	v_lshrrev_b32_e32 v2, 22, v2
	v_add_u32_e32 v2, v1, v2
	v_ashrrev_i32_e32 v2, 10, v2
	v_mul_i32_i24_e32 v4, 0x400, v2
	v_sub_u32_e32 v1, v1, v4
	v_lshrrev_b32_e32 v4, 4, v1
	v_bitop3_b32 v1, v4, v1, 32 bitop3:0x6c
	v_ashrrev_i32_e32 v5, 31, v1
	v_lshrrev_b32_e32 v5, 26, v5
	s_ashr_i32 s3, s2, 31
	v_lshlrev_b32_e32 v4, 3, v2
	v_add_u32_e32 v5, v1, v5
	s_lshl_b64 s[8:9], s[2:3], 9
	s_ashr_i32 s5, s85, 31
	v_and_b32_e32 v4, -16, v4
	v_ashrrev_i32_e32 v6, 6, v5
	v_lshlrev_b32_e32 v2, 5, v2
	s_mul_i32 s5, s8, s5
	s_mul_hi_u32 s10, s8, s85
	s_ashr_i32 s12, s95, 31
	v_add_u32_e32 v4, v6, v4
	v_and_b32_e32 v18, 32, v2
	v_and_b32_e32 v2, 0xc0, v5
	v_and_b32_e32 v5, 3, v6
	s_add_i32 s5, s10, s5
	s_lshr_b64 s[10:11], s[2:3], 23
	s_mul_i32 s12, s8, s12
	s_mul_hi_u32 s13, s8, s95
	v_and_or_b32 v5, v4, s1, v5
	s_ashr_i32 s1, s4, 6
	s_mul_i32 s11, s10, s85
	s_add_i32 s12, s13, s12
	s_mul_i32 s10, s10, s95
	s_ashr_i32 s0, s4, 8
	v_sub_u32_e32 v1, v1, v2
	s_lshl_b64 s[6:7], s[2:3], 8
	s_lshl_b32 s54, s1, 10
	s_add_i32 s5, s5, s11
	s_add_i32 s12, s12, s10
	s_mul_i32 s10, s8, s95
	v_readlane_b32 s14, v245, 18
	v_ashrrev_i16_sdwa v1, v3, sext(v1) dst_sel:DWORD dst_unused:UNUSED_PAD src0_sel:DWORD src1_sel:BYTE_0
	v_lshlrev_b32_e32 v2, 1, v4
	v_lshrrev_b32_e32 v3, 2, v4
	v_readlane_b32 s15, v245, 19
	s_add_u32 s50, s14, s10
	v_and_b32_e32 v2, 24, v2
	v_and_b32_e32 v3, 4, v3
	s_addc_u32 s51, s15, s12
	s_cmp_lt_i32 s95, 3
	s_cselect_b32 s98, 0, 0x200
	s_add_u32 s50, s50, s98
	s_addc_u32 s51, s51, 0
	s_add_i32 s55, s54, 0
	v_bfe_i32 v19, v1, 0, 16
	v_or3_b32 v2, v5, v3, v2
	s_add_i32 m0, s55, 0x10000
	v_add_u32_e32 v1, v18, v19
	v_mul_lo_u32 v2, v2, s2
	global_load_lds_dwordx4 v222, s[50:51]
	s_add_i32 m0, s55, 0x12000
	v_add_lshl_u32 v226, v2, v1, 1
	s_add_u32 s12, s50, s6
	global_load_lds_dwordx4 v226, s[50:51]
	s_addc_u32 s13, s51, s7
	s_add_i32 m0, s55, 0x14000
	s_mul_i32 s11, s8, s85
	global_load_lds_dwordx4 v222, s[12:13]
	s_add_i32 m0, s55, 0x16000
	s_add_u32 s48, s21, s11
	s_addc_u32 s49, s34, s5
	s_cmp_lt_i32 s95, 3
	s_cselect_b32 s98, 0, 0x200
	s_add_u32 s48, s48, s98
	s_addc_u32 s49, s49, 0
	s_add_i32 s56, s55, 0x2000
	v_mul_lo_u32 v20, v4, s2
	global_load_lds_dwordx4 v226, s[12:13]
	s_mov_b32 m0, s55
	s_add_u32 s10, s48, s6
	v_add_lshl_u32 v224, v1, v20, 1
	global_load_lds_dwordx4 v220, s[48:49]
	s_mov_b32 m0, s56
	s_addc_u32 s11, s49, s7
	s_add_i32 s57, s55, 0x4000
	global_load_lds_dwordx4 v224, s[48:49]
	s_mov_b32 m0, s57
	s_add_i32 s58, s55, 0x6000
	global_load_lds_dwordx4 v220, s[10:11]
	s_mov_b32 m0, s58
	v_mov_b32_e32 v229, 0
	global_load_lds_dwordx4 v224, s[10:11]
	v_mov_b32_e32 v223, v229
	v_mov_b32_e32 v227, v229
	v_mov_b32_e32 v221, v229
	v_mov_b32_e32 v225, v229
	s_cmp_eq_u32 s0, 1
	s_mov_b32 s11, 0
	v_lshl_add_u64 v[10:11], s[50:51], 0, v[222:223]
	v_lshl_add_u64 v[6:7], s[50:51], 0, v[226:227]
	v_lshl_add_u64 v[4:5], s[12:13], 0, v[222:223]
	v_lshl_add_u64 v[2:3], s[12:13], 0, v[226:227]
	v_lshl_add_u64 v[8:9], s[48:49], 0, v[220:221]
	s_cselect_b64 s[12:13], -1, 0
	s_cmp_lg_u32 s0, 1
	v_lshl_add_u64 v[12:13], s[48:49], 0, v[224:225]
	s_cbranch_scc1 .LBB0_1749
	s_barrier

.LBB0_1754:
	s_nop 0
	v_cndmask_b32_e64 v2, 0, 1, s[4:5]
	v_cmp_ne_u32_e64 s[2:3], 1, v2
	s_andn2_b64 vcc, exec, s[4:5]
	s_mov_b64 s[4:5], s[48:49]
	s_cbranch_vccnz .LBB0_1756
	s_ashr_i32 s0, s94, 31
	s_mul_hi_u32 s1, s8, s94
	s_mul_i32 s0, s8, s0
	s_add_i32 s0, s1, s0
	s_mul_i32 s1, s9, s94
	s_add_i32 s0, s0, s1
	s_mul_i32 s1, s8, s94
	s_add_u32 s4, s21, s1
	s_addc_u32 s5, s34, s0
	s_cmp_lt_i32 s84, 3
	s_cselect_b32 s98, 0, 0x200
	s_add_u32 s4, s4, s98
	s_addc_u32 s5, s5, 0
.LBB0_1756:
	s_and_b64 vcc, exec, s[2:3]
	s_mov_b64 s[46:47], s[50:51]
	s_cbranch_vccnz .LBB0_1758
	s_ashr_i32 s0, s84, 31
	s_mul_hi_u32 s1, s8, s84
	s_mul_i32 s0, s8, s0
	s_add_i32 s0, s1, s0
	s_mul_i32 s1, s9, s84
	s_add_i32 s0, s0, s1
	s_mul_i32 s1, s8, s84
	v_readlane_b32 s38, v245, 18
	v_readlane_b32 s39, v245, 19
	s_add_u32 s46, s38, s1
	s_addc_u32 s47, s39, s0
	s_cmp_lt_i32 s84, 3
	s_cselect_b32 s98, 0, 0x200
	s_add_u32 s46, s46, s98
	s_addc_u32 s47, s47, 0
.LBB0_1758:
	v_mov_b32_e32 v3, v0
	v_mov_b64_e32 v[194:195], v[2:3]
	v_mov_b64_e32 v[172:173], v[2:3]
	v_mov_b64_e32 v[150:151], v[2:3]
	v_mov_b64_e32 v[196:197], v[2:3]
	v_mov_b64_e32 v[174:175], v[2:3]
	v_mov_b64_e32 v[152:153], v[2:3]
	v_mov_b64_e32 v[216:217], v[2:3]
	v_mov_b64_e32 v[210:211], v[2:3]
	v_mov_b64_e32 v[204:205], v[2:3]
	v_mov_b64_e32 v[166:167], v[2:3]
	v_mov_b64_e32 v[160:161], v[2:3]
	v_mov_b64_e32 v[198:199], v[2:3]
	v_mov_b64_e32 v[188:189], v[2:3]
	v_mov_b64_e32 v[182:183], v[2:3]
	v_mov_b64_e32 v[176:177], v[2:3]
	v_mov_b64_e32 v[154:155], v[2:3]
	v_mov_b64_e32 v[144:145], v[2:3]
	v_mov_b64_e32 v[138:139], v[2:3]
	v_mov_b64_e32 v[132:133], v[2:3]
	v_mov_b64_e32 v[218:219], v[2:3]
	v_mov_b64_e32 v[212:213], v[2:3]
	v_mov_b64_e32 v[206:207], v[2:3]
	v_mov_b64_e32 v[168:169], v[2:3]
	v_mov_b64_e32 v[162:163], v[2:3]
	v_mov_b64_e32 v[200:201], v[2:3]
	v_mov_b64_e32 v[190:191], v[2:3]
	v_mov_b64_e32 v[184:185], v[2:3]
	v_mov_b64_e32 v[178:179], v[2:3]
	v_mov_b64_e32 v[156:157], v[2:3]
	v_mov_b64_e32 v[146:147], v[2:3]
	v_mov_b64_e32 v[140:141], v[2:3]
	v_mov_b64_e32 v[134:135], v[2:3]
	s_andn2_b64 vcc, exec, s[16:17]
	v_mov_b32_e32 v129, v0
	v_mov_b32_e32 v128, v0
	v_mov_b32_e32 v127, v0
	v_mov_b32_e32 v125, v0
	v_mov_b32_e32 v124, v0
	v_mov_b32_e32 v123, v0
	v_mov_b32_e32 v121, v0
	v_mov_b32_e32 v120, v0
	v_mov_b32_e32 v119, v0
	v_mov_b32_e32 v117, v0
	v_mov_b32_e32 v116, v0
	v_mov_b32_e32 v115, v0
	v_mov_b32_e32 v113, v0
	v_mov_b32_e32 v112, v0
	v_mov_b32_e32 v111, v0
	v_mov_b32_e32 v109, v0
	v_mov_b32_e32 v108, v0
	v_mov_b32_e32 v107, v0
	v_mov_b32_e32 v105, v0
	v_mov_b32_e32 v104, v0
	v_mov_b32_e32 v103, v0
	v_mov_b32_e32 v101, v0
	v_mov_b32_e32 v100, v0
	v_mov_b32_e32 v99, v0
	v_mov_b32_e32 v65, v0
	v_mov_b32_e32 v64, v0
	v_mov_b32_e32 v63, v0
	v_mov_b32_e32 v61, v0
	v_mov_b32_e32 v60, v0
	v_mov_b32_e32 v59, v0
	v_mov_b32_e32 v57, v0
	v_mov_b32_e32 v56, v0
	v_mov_b32_e32 v55, v0
	v_mov_b32_e32 v53, v0
	v_mov_b32_e32 v52, v0
	v_mov_b32_e32 v51, v0
	v_mov_b32_e32 v49, v0
	v_mov_b32_e32 v48, v0
	v_mov_b32_e32 v47, v0
	v_mov_b32_e32 v45, v0
	v_mov_b32_e32 v44, v0
	v_mov_b32_e32 v43, v0
	v_mov_b32_e32 v41, v0
	v_mov_b32_e32 v40, v0
	v_mov_b32_e32 v39, v0
	v_mov_b32_e32 v37, v0
	v_mov_b32_e32 v36, v0
	v_mov_b32_e32 v35, v0
	v_mov_b32_e32 v97, v0
	v_mov_b32_e32 v96, v0
	v_mov_b32_e32 v95, v0
	v_mov_b32_e32 v93, v0
	v_mov_b32_e32 v92, v0
	v_mov_b32_e32 v91, v0
	v_mov_b32_e32 v89, v0
	v_mov_b32_e32 v88, v0
	v_mov_b32_e32 v87, v0
	v_mov_b32_e32 v85, v0
	v_mov_b32_e32 v84, v0
	v_mov_b32_e32 v83, v0
	v_mov_b32_e32 v81, v0
	v_mov_b32_e32 v80, v0
	v_mov_b32_e32 v79, v0
	v_mov_b32_e32 v77, v0
	v_mov_b32_e32 v76, v0
	v_mov_b32_e32 v75, v0
	v_mov_b32_e32 v73, v0
	v_mov_b32_e32 v72, v0
	v_mov_b32_e32 v71, v0
	v_mov_b32_e32 v69, v0
	v_mov_b32_e32 v68, v0
	v_mov_b32_e32 v67, v0
	v_mov_b32_e32 v33, v0
	v_mov_b32_e32 v32, v0
	v_mov_b32_e32 v31, v0
	v_mov_b32_e32 v29, v0
	v_mov_b32_e32 v28, v0
	v_mov_b32_e32 v27, v0
	v_mov_b32_e32 v25, v0
	v_mov_b32_e32 v24, v0
	v_mov_b32_e32 v23, v0
	v_mov_b32_e32 v21, v0
	v_mov_b32_e32 v20, v0
	v_mov_b32_e32 v19, v0
	v_mov_b32_e32 v17, v0
	v_mov_b32_e32 v16, v0
	v_mov_b32_e32 v15, v0
	v_mov_b32_e32 v13, v0
	v_mov_b32_e32 v12, v0
	v_mov_b32_e32 v11, v0
	v_mov_b32_e32 v9, v0
	v_mov_b32_e32 v8, v0
	v_mov_b32_e32 v7, v0
	v_mov_b32_e32 v5, v0
	v_mov_b32_e32 v4, v0
	v_mov_b64_e32 v[214:215], v[0:1]
	v_mov_b64_e32 v[216:217], v[0:1]
	v_mov_b64_e32 v[208:209], v[0:1]
	v_mov_b64_e32 v[210:211], v[0:1]
	v_mov_b64_e32 v[202:203], v[0:1]
	v_mov_b64_e32 v[204:205], v[0:1]
	v_mov_b64_e32 v[192:193], v[0:1]
	v_mov_b64_e32 v[194:195], v[0:1]
	v_mov_b64_e32 v[170:171], v[0:1]
	v_mov_b64_e32 v[172:173], v[0:1]
	v_mov_b64_e32 v[164:165], v[0:1]
	v_mov_b64_e32 v[166:167], v[0:1]
	v_mov_b64_e32 v[158:159], v[0:1]
	v_mov_b64_e32 v[160:161], v[0:1]
	v_mov_b64_e32 v[148:149], v[0:1]
	v_mov_b64_e32 v[150:151], v[0:1]
	v_mov_b64_e32 v[196:197], v[0:1]
	v_mov_b64_e32 v[198:199], v[0:1]
	v_mov_b64_e32 v[186:187], v[0:1]
	v_mov_b64_e32 v[188:189], v[0:1]
	v_mov_b64_e32 v[180:181], v[0:1]
	v_mov_b64_e32 v[182:183], v[0:1]
	v_mov_b64_e32 v[174:175], v[0:1]
	v_mov_b64_e32 v[176:177], v[0:1]
	v_mov_b64_e32 v[152:153], v[0:1]
	v_mov_b64_e32 v[154:155], v[0:1]
	v_mov_b64_e32 v[142:143], v[0:1]
	v_mov_b64_e32 v[144:145], v[0:1]
	v_mov_b64_e32 v[136:137], v[0:1]
	v_mov_b64_e32 v[138:139], v[0:1]
	v_mov_b64_e32 v[130:131], v[0:1]
	v_mov_b64_e32 v[132:133], v[0:1]
	s_cbranch_vccnz .LBB0_1762
	s_add_u32 s48, s48, 0x80
	s_addc_u32 s49, s49, 0
	s_add_u32 s0, s50, 0x100
	s_addc_u32 s1, s51, 0
	s_mov_b32 s10, 0
	s_cmp_lt_i32 s95, 3
	s_cselect_b32 s61, 4, 2
	s_add_i32 s62, s61, -2
	v_mov_b32_e32 v2, v0
	v_mov_b32_e32 v3, v0
	v_mov_b32_e32 v4, v0
	v_mov_b32_e32 v5, v0
	v_mov_b32_e32 v6, v0
	v_mov_b32_e32 v7, v0
	v_mov_b32_e32 v8, v0
	v_mov_b32_e32 v9, v0
	v_mov_b32_e32 v10, v0
	v_mov_b32_e32 v11, v0
	v_mov_b32_e32 v12, v0
	v_mov_b32_e32 v13, v0
	v_mov_b32_e32 v14, v0
	v_mov_b32_e32 v15, v0
	v_mov_b32_e32 v16, v0
	v_mov_b32_e32 v17, v0
	v_mov_b32_e32 v18, v0
	v_mov_b32_e32 v19, v0
	v_mov_b32_e32 v20, v0
	v_mov_b32_e32 v21, v0
	v_mov_b32_e32 v22, v0
	v_mov_b32_e32 v23, v0
	v_mov_b32_e32 v24, v0
	v_mov_b32_e32 v25, v0
	v_mov_b32_e32 v26, v0
	v_mov_b32_e32 v27, v0
	v_mov_b32_e32 v28, v0
	v_mov_b32_e32 v29, v0
	v_mov_b32_e32 v30, v0
	v_mov_b32_e32 v31, v0
	v_mov_b32_e32 v32, v0
	v_mov_b32_e32 v33, v0
	v_mov_b32_e32 v66, v0
	v_mov_b32_e32 v67, v0
	v_mov_b32_e32 v68, v0
	v_mov_b32_e32 v69, v0
	v_mov_b32_e32 v70, v0
	v_mov_b32_e32 v71, v0
	v_mov_b32_e32 v72, v0
	v_mov_b32_e32 v73, v0
	v_mov_b32_e32 v74, v0
	v_mov_b32_e32 v75, v0
	v_mov_b32_e32 v76, v0
	v_mov_b32_e32 v77, v0
	v_mov_b32_e32 v78, v0
	v_mov_b32_e32 v79, v0
	v_mov_b32_e32 v80, v0
	v_mov_b32_e32 v81, v0
	v_mov_b32_e32 v82, v0
	v_mov_b32_e32 v83, v0
	v_mov_b32_e32 v84, v0
	v_mov_b32_e32 v85, v0
	v_mov_b32_e32 v86, v0
	v_mov_b32_e32 v87, v0
	v_mov_b32_e32 v88, v0
	v_mov_b32_e32 v89, v0
	v_mov_b32_e32 v90, v0
	v_mov_b32_e32 v91, v0
	v_mov_b32_e32 v92, v0
	v_mov_b32_e32 v93, v0
	v_mov_b32_e32 v94, v0
	v_mov_b32_e32 v95, v0
	v_mov_b32_e32 v96, v0
	v_mov_b32_e32 v97, v0
	v_mov_b32_e32 v34, v0
	v_mov_b32_e32 v35, v0
	v_mov_b32_e32 v36, v0
	v_mov_b32_e32 v37, v0
	v_mov_b32_e32 v38, v0
	v_mov_b32_e32 v39, v0
	v_mov_b32_e32 v40, v0
	v_mov_b32_e32 v41, v0
	v_mov_b32_e32 v42, v0
	v_mov_b32_e32 v43, v0
	v_mov_b32_e32 v44, v0
	v_mov_b32_e32 v45, v0
	v_mov_b32_e32 v46, v0
	v_mov_b32_e32 v47, v0
	v_mov_b32_e32 v48, v0
	v_mov_b32_e32 v49, v0
	v_mov_b32_e32 v50, v0
	v_mov_b32_e32 v51, v0
	v_mov_b32_e32 v52, v0
	v_mov_b32_e32 v53, v0
	v_mov_b32_e32 v54, v0
	v_mov_b32_e32 v55, v0
	v_mov_b32_e32 v56, v0
	v_mov_b32_e32 v57, v0
	v_mov_b32_e32 v58, v0
	v_mov_b32_e32 v59, v0
	v_mov_b32_e32 v60, v0
	v_mov_b32_e32 v61, v0
	v_mov_b32_e32 v62, v0
	v_mov_b32_e32 v63, v0
	v_mov_b32_e32 v64, v0
	v_mov_b32_e32 v65, v0
	v_mov_b32_e32 v98, v0
	v_mov_b32_e32 v99, v0
	v_mov_b32_e32 v100, v0
	v_mov_b32_e32 v101, v0
	v_mov_b32_e32 v102, v0
	v_mov_b32_e32 v103, v0
	v_mov_b32_e32 v104, v0
	v_mov_b32_e32 v105, v0
	v_mov_b32_e32 v106, v0
	v_mov_b32_e32 v107, v0
	v_mov_b32_e32 v108, v0
	v_mov_b32_e32 v109, v0
	v_mov_b32_e32 v110, v0
	v_mov_b32_e32 v111, v0
	v_mov_b32_e32 v112, v0
	v_mov_b32_e32 v113, v0
	v_mov_b32_e32 v114, v0
	v_mov_b32_e32 v115, v0
	v_mov_b32_e32 v116, v0
	v_mov_b32_e32 v117, v0
	v_mov_b32_e32 v118, v0
	v_mov_b32_e32 v119, v0
	v_mov_b32_e32 v120, v0
	v_mov_b32_e32 v121, v0
	v_mov_b32_e32 v122, v0
	v_mov_b32_e32 v123, v0
	v_mov_b32_e32 v124, v0
	v_mov_b32_e32 v125, v0
	v_mov_b32_e32 v126, v0
	v_mov_b32_e32 v127, v0
	v_mov_b32_e32 v128, v0
	v_mov_b32_e32 v129, v0
